# K-tile LDS-DMA issued after the K-fragment ds_reads; post-QK filler trimmed to the exact 12 wait states
# speedup vs baseline: 1.0090x; 1.0005x over previous
.Latt_top2:
	global_load_dwordx4 v[128:131], v[172:173], off
	s_add_i32 s67, s67, 1
	s_and_b32 s68, s67, 1
	s_cmp_gt_i32 s67, s66
	s_cbranch_scc1 .Latt_wonly
	s_mul_i32 s50, s68, 0x3400
	v_add_u32_e32 v52, s50, v189
	ds_read_b128 v[48:51], v52
	ds_read_b128 v[132:135], v52 offset:32
	ds_read_b128 v[136:139], v52 offset:6656
	ds_read_b128 v[140:143], v52 offset:6688
	ds_read_b128 v[144:147], v52 offset:64
	ds_read_b128 v[148:151], v52 offset:96
	ds_read_b128 v[152:155], v52 offset:6720
	ds_read_b128 v[156:159], v52 offset:6752
	ds_read_b128 v[160:163], v52 offset:128
	ds_read_b128 v[192:195], v52 offset:160
	ds_read_b128 v[196:199], v52 offset:6784
	ds_read_b128 v[200:203], v52 offset:6816
	s_cmpk_ge_u32 s64, 0xe0
	s_cbranch_scc1 .Lkdma_done_la
	s_xor_b32 s69, s68, 1
	s_mul_i32 s69, s69, 0x3400
	s_lshl_b32 s50, s64, 6
	s_add_i32 s69, s69, s50
	s_mov_b32 m0, s69
	s_nop 0
	global_load_lds_dwordx4 v[204:205], off
	v_lshl_add_u64 v[204:205], v[204:205], 0, v[220:221]
	s_cmpk_ge_u32 s64, 0xc0
	s_cbranch_scc1 .Lkdma_done_la
	s_add_i32 m0, s69, 0x400
	s_nop 0
	global_load_lds_dwordx4 v[206:207], off
	v_lshl_add_u64 v[206:207], v[206:207], 0, v[222:223]
.Lkdma_done_la:
	s_waitcnt lgkmcnt(11)
	v_mfma_f32_32x32x16_bf16 v[64:79], v[48:51], v[104:107], v[32:47]
	s_mul_i32 s50, s68, 0x2400
	s_waitcnt lgkmcnt(9)
	v_mfma_f32_32x32x16_bf16 v[48:63], v[136:139], v[104:107], v[32:47]
	v_mfma_f32_32x32x16_bf16 v[64:79], v[132:135], v[100:103], v[64:79]
	v_add_u32_e32 v132, s50, v165
	v_add_u32_e32 v133, 0x6800, v132
	v_add_u32_e32 v132, 0x7800, v132
	s_waitcnt lgkmcnt(8)
	v_mfma_f32_32x32x16_bf16 v[48:63], v[140:143], v[100:103], v[48:63]
	s_waitcnt lgkmcnt(7)
	v_mfma_f32_32x32x16_bf16 v[64:79], v[144:147], v[96:99], v[64:79]
	s_waitcnt lgkmcnt(5)
	v_mfma_f32_32x32x16_bf16 v[48:63], v[152:155], v[96:99], v[48:63]
	ds_read_b128 v[152:155], v133 offset:32
	v_mfma_f32_32x32x16_bf16 v[64:79], v[148:151], v[92:95], v[64:79]
	s_waitcnt lgkmcnt(5)
	v_mfma_f32_32x32x16_bf16 v[48:63], v[156:159], v[92:95], v[48:63]
	s_waitcnt lgkmcnt(4)
	v_mfma_f32_32x32x16_bf16 v[64:79], v[160:163], v[88:91], v[64:79]
	ds_read_b128 v[160:163], v133
	ds_read_b128 v[156:159], v132 offset:512
	ds_read_b128 v[148:151], v132 offset:544
	ds_read_b128 v[144:147], v133 offset:64
	ds_read_b128 v[140:143], v132 offset:576
	ds_read_b128 v[136:139], v133 offset:96
	ds_read_b128 v[132:135], v132 offset:608
	s_waitcnt lgkmcnt(9)
	v_mfma_f32_32x32x16_bf16 v[48:63], v[196:199], v[88:91], v[48:63]
	v_mfma_f32_32x32x16_bf16 v[64:79], v[192:195], v[84:87], v[64:79]
	s_waitcnt lgkmcnt(8)
	v_mfma_f32_32x32x16_bf16 v[48:63], v[200:203], v[84:87], v[48:63]
	s_xor_b32 s68, s68, 1
	s_mulk_i32 s68, 0x2400
	v_add_u32_e32 v191, s68, v188
	v_lshl_add_u64 v[172:173], v[172:173], 0, s[18:19]
	ds_write2_b64 v191, v[116:117], v[118:119] offset1:2
	s_nop 4
	v_max_f32_e32 v191, v65, v65
	v_max_f32_e32 v192, v64, v64
	v_max_f32_e32 v191, v192, v191
	v_max3_f32 v192, v66, v67, v49
	v_max3_f32 v191, v191, v48, v50
	v_max3_f32 v191, v191, v51, v68
	v_max3_f32 v192, v192, v70, v71
	v_max3_f32 v191, v191, v69, v52
	v_max3_f32 v192, v192, v54, v55
	v_max3_f32 v191, v191, v53, v72
	v_max3_f32 v192, v192, v74, v75
	v_max3_f32 v191, v191, v73, v56
	v_max3_f32 v192, v192, v58, v59
	v_max3_f32 v191, v191, v57, v76
	v_max3_f32 v192, v192, v78, v79
	v_max3_f32 v191, v191, v77, v60
	v_max3_f32 v192, v192, v62, v63
	v_max3_f32 v191, v191, v61, v192
	v_mov_b32_e32 v192, v191
	s_nop 1
	v_permlane32_swap_b32_e32 v191, v192
	v_max_f32_e32 v191, v191, v192
	v_cmp_lt_f32_e32 vcc, s3, v191
	s_cbranch_vccz .LBB0_747
	v_max_f32_e32 v32, v191, v191
	v_max_f32_e32 v34, 0, v32
	v_exp_f32_e64 v191, -v34
	s_and_saveexec_b64 s[50:51], s[46:47]
	ds_write_b32 v190, v191 offset:45056
	s_or_b64 exec, exec, s[50:51]
	v_add_u32_e32 v47, s16, v166
	ds_read_b128 v[192:195], v47 offset:45120
	ds_read_b128 v[196:199], v47 offset:45152
	ds_read_b128 v[200:203], v47 offset:45056
	ds_read_b128 v[204:207], v47 offset:45088
	v_add_f32_e32 v82, v82, v34
	v_xor_b32_e32 v32, 0x80000000, v82
	v_pk_add_f32 v[64:65], v[64:65], v[34:35] op_sel_hi:[1,0] neg_lo:[0,1] neg_hi:[0,1]
	v_pk_add_f32 v[48:49], v[48:49], v[34:35] op_sel_hi:[1,0] neg_lo:[0,1] neg_hi:[0,1]
	v_pk_add_f32 v[66:67], v[66:67], v[34:35] op_sel_hi:[1,0] neg_lo:[0,1] neg_hi:[0,1]
	v_pk_add_f32 v[50:51], v[50:51], v[34:35] op_sel_hi:[1,0] neg_lo:[0,1] neg_hi:[0,1]
	v_pk_add_f32 v[68:69], v[68:69], v[34:35] op_sel_hi:[1,0] neg_lo:[0,1] neg_hi:[0,1]
	v_pk_add_f32 v[52:53], v[52:53], v[34:35] op_sel_hi:[1,0] neg_lo:[0,1] neg_hi:[0,1]
	v_pk_add_f32 v[70:71], v[70:71], v[34:35] op_sel_hi:[1,0] neg_lo:[0,1] neg_hi:[0,1]
	v_pk_add_f32 v[54:55], v[54:55], v[34:35] op_sel_hi:[1,0] neg_lo:[0,1] neg_hi:[0,1]
	v_pk_add_f32 v[72:73], v[72:73], v[34:35] op_sel_hi:[1,0] neg_lo:[0,1] neg_hi:[0,1]
	v_pk_add_f32 v[56:57], v[56:57], v[34:35] op_sel_hi:[1,0] neg_lo:[0,1] neg_hi:[0,1]
	v_pk_add_f32 v[74:75], v[74:75], v[34:35] op_sel_hi:[1,0] neg_lo:[0,1] neg_hi:[0,1]
	v_pk_add_f32 v[58:59], v[58:59], v[34:35] op_sel_hi:[1,0] neg_lo:[0,1] neg_hi:[0,1]
	v_pk_add_f32 v[76:77], v[76:77], v[34:35] op_sel_hi:[1,0] neg_lo:[0,1] neg_hi:[0,1]
	v_pk_add_f32 v[60:61], v[60:61], v[34:35] op_sel_hi:[1,0] neg_lo:[0,1] neg_hi:[0,1]
	v_pk_add_f32 v[78:79], v[78:79], v[34:35] op_sel_hi:[1,0] neg_lo:[0,1] neg_hi:[0,1]
	v_pk_add_f32 v[62:63], v[62:63], v[34:35] op_sel_hi:[1,0] neg_lo:[0,1] neg_hi:[0,1]
	v_mov_b32_e32 v33, v32
	v_mov_b32_e32 v34, v32
	v_mov_b32_e32 v35, v32
	v_mov_b32_e32 v36, v32
	v_mov_b32_e32 v37, v32
	v_mov_b32_e32 v38, v32
	v_mov_b32_e32 v39, v32
	v_mov_b32_e32 v40, v32
	v_mov_b32_e32 v41, v32
	v_mov_b32_e32 v42, v32
	v_mov_b32_e32 v43, v32
	v_mov_b32_e32 v44, v32
	v_mov_b32_e32 v45, v32
	v_mov_b32_e32 v46, v32
	v_mov_b32_e32 v47, v32
	v_mul_f32_e32 v83, v83, v191
	s_waitcnt lgkmcnt(2)
	v_pk_mul_f32 v[12:13], v[12:13], v[196:197]
	v_pk_mul_f32 v[8:9], v[8:9], v[192:193]
	s_waitcnt lgkmcnt(0)
	v_pk_mul_f32 v[4:5], v[4:5], v[204:205]
	v_pk_mul_f32 v[14:15], v[14:15], v[198:199]
	v_pk_mul_f32 v[10:11], v[10:11], v[194:195]
	v_pk_mul_f32 v[6:7], v[6:7], v[206:207]
	v_pk_mul_f32 v[2:3], v[2:3], v[202:203]
	v_pk_mul_f32 v[0:1], v[0:1], v[200:201]
	v_pk_mul_f32 v[28:29], v[28:29], v[196:197]
	v_pk_mul_f32 v[24:25], v[24:25], v[192:193]
	v_pk_mul_f32 v[20:21], v[20:21], v[204:205]
	v_pk_mul_f32 v[30:31], v[30:31], v[198:199]
	v_pk_mul_f32 v[26:27], v[26:27], v[194:195]
	v_pk_mul_f32 v[22:23], v[22:23], v[206:207]
	v_pk_mul_f32 v[18:19], v[18:19], v[202:203]
	v_pk_mul_f32 v[16:17], v[16:17], v[200:201]

.Latt_wonly:
	s_cmpk_ge_u32 s64, 0xe0
	s_cbranch_scc1 .Lkdma_done_lb
	s_xor_b32 s69, s68, 1
	s_mul_i32 s69, s69, 0x3400
	s_lshl_b32 s50, s64, 6
	s_add_i32 s69, s69, s50
	s_mov_b32 m0, s69
	s_nop 0
	global_load_lds_dwordx4 v[204:205], off
	v_lshl_add_u64 v[204:205], v[204:205], 0, v[220:221]
	s_cmpk_ge_u32 s64, 0xc0
	s_cbranch_scc1 .Lkdma_done_lb
	s_add_i32 m0, s69, 0x400
	s_nop 0
	global_load_lds_dwordx4 v[206:207], off
	v_lshl_add_u64 v[206:207], v[206:207], 0, v[222:223]
